# cross-attention QK k-loop: fragment reads ordered by first use with counted lgkmcnt waits (9/6/3/0): first MFMA after 3 reads instead of 5
# speedup vs baseline: 1.0041x; 1.0041x over previous
; template <bool DIFF> ...
;     ...
; #pragma unroll 1
;             for (int kq = 0; kq < NKS; kq += 4) {
;                 bf16x8 ka0[4], ka1[4], qq[4];
; #pragma unroll
;                 for (int j = 0; j < 4; ++j) {
;                     if (DIFF) { const int ko = 256 * l32 + 16 * (((c << 3) + 2 * j + hi) ^ (((l32 & 3) << 2) | ((l32 >> 2) & 3)));
;                         ka0[j] = *(LAS const bf16x8*)(kb + ko); ka1[j] = *(LAS const bf16x8*)(kb + 8192 + ko); }
;                     else { ka0[j] = *(LAS const bf16x8*)(ka + (kq + j) * 32); ka1[j] = *(LAS const bf16x8*)(ka + 32 * KSTR + (kq + j) * 32); }
;                     qq[j] = DIFF ? qf[DIFF ? j : 0] : *(LAS const bf16x8*)(qa + (kq + j) * 32); }
;                 __builtin_amdgcn_sched_barrier(0);
; #pragma unroll
;                 for (int j = 0; j < 4; ++j) { s0 = __builtin_amdgcn_mfma_f32_32x32x16_bf16(ka0[j], qq[j], s0, 0, 0, 0); s1 = __builtin_amdgcn_mfma_f32_32x32x16_bf16(ka1[j], qq[j], s1, 0, 0, 0); }
;             }
;             float c0 = 0.f, c1 = 0.f;
;             if (DIFF) {
;                 c0 = sl2 * (float)(64 * kt - wrow); c1 = sl2 * (float)(64 * kt + 32 - wrow);
;                 if (64 * kt + 64 > wrow) {
;                     asm volatile("" ::: "memory");
;                     const int irel = wrow + l32 - 64 * kt - hi * 4;
; #pragma unroll
;                     for (int r = 0; r < 16; ++r) { const int cr = (r >> 2) * 8 + (r & 3); if (cr > irel) s0[r] = -INFINITY; if (cr + 32 > irel) s1[r] = -INFINITY; }
;                 }
;             }
;             LAS const unsigned char* va = vb + (hi * 4 + ((lane & 15) >> 2)) * VSTR + (DIFF ? 0 : c * 256) + (((lane >> 4) & 1) * 16 + 4 * (lane & 3)) * 2;
;             bf16x8 fa[4], fb[4];
;             const int vq = (lane & 15) >> 2, vp = lane & 3, vg1 = (lane >> 4) & 1;
;             const int vs0 = 256 * (hi * 4 + vq) + 16 * ((2 * vg1 + (vp >> 1)) ^ hi) + 8 * (vp & 1), vs1 = 256 * (hi * 4 + 8 + vq) + 16 * ((2 * vg1 + (vp >> 1)) ^ (hi + 2)) + 8 * (vp & 1);
;     ...
;             float mx0 = s0[0], mx1 = s1[0];
; #pragma unroll
;             for (int r = 1; r < 16; r += 2) { mx0 = fmaxf(fmaxf(mx0, s0[r]), s0[r + 1 < 16 ? r + 1 : r]); mx1 = fmaxf(fmaxf(mx1, s1[r]), s1[r + 1 < 16 ? r + 1 : r]); }
;             float mx = fmaxf(__builtin_fmaf(mx0, sc2, c0), __builtin_fmaf(mx1, sc2, c1));
;             mx = fmaxf(mx, __shfl_xor(mx, 32));
.LBB0_256:
	v_add_u32_e32 v176, v146, v200
	v_add_u32_e32 v147, v0, v200
	v_add_u32_e32 v164, 0x11400, v176
	v_add_u32_e32 v168, 0x11420, v176
	v_add_u32_e32 v177, 0x11440, v176
	v_add_u32_e32 v236, 0x11460, v176
	ds_read_b128 v[164:167], v164
	ds_read_b128 v[148:151], v147
	ds_read_b128 v[156:159], v147 offset:16896
	ds_read_b128 v[168:171], v168
	ds_read_b128 v[152:155], v147 offset:32
	ds_read_b128 v[160:163], v147 offset:16928
	ds_read_b128 v[222:225], v177
	ds_read_b128 v[172:175], v147 offset:64
	ds_read_b128 v[214:217], v147 offset:16960
	ds_read_b128 v[226:229], v236
	ds_read_b128 v[210:213], v147 offset:96
	ds_read_b128 v[218:221], v147 offset:16992
	s_waitcnt lgkmcnt(9)
	v_mfma_f32_32x32x16_bf16 v[98:113], v[148:151], v[164:167], v[98:113]
	s_add_i32 s18, s18, 4
	v_add_u32_e32 v146, 0x80, v146
	v_add_u32_e32 v0, 0x80, v0
	s_cmp_gt_u32 s18, 11
	v_mfma_f32_32x32x16_bf16 v[82:97], v[156:159], v[164:167], v[82:97]
	s_waitcnt lgkmcnt(6)
	v_mfma_f32_32x32x16_bf16 v[98:113], v[152:155], v[168:171], v[98:113]
	v_mfma_f32_32x32x16_bf16 v[82:97], v[160:163], v[168:171], v[82:97]
	s_waitcnt lgkmcnt(3)
	v_mfma_f32_32x32x16_bf16 v[98:113], v[172:175], v[222:225], v[98:113]
	v_mfma_f32_32x32x16_bf16 v[82:97], v[214:217], v[222:225], v[82:97]
	s_waitcnt lgkmcnt(0)
	v_mfma_f32_32x32x16_bf16 v[98:113], v[210:213], v[226:229], v[98:113]
	v_mfma_f32_32x32x16_bf16 v[82:97], v[218:221], v[226:229], v[82:97]
	s_cbranch_scc0 .LBB0_256
	ds_read_b64_tr_b16 v[162:163], v204 offset:33792
	ds_read_b64_tr_b16 v[164:165], v204 offset:38400
	ds_read_b64_tr_b16 v[148:149], v204 offset:38464
	ds_read_b64_tr_b16 v[146:147], v204 offset:33856
	ds_read_b64_tr_b16 v[166:167], v204 offset:43008
	ds_read_b64_tr_b16 v[168:169], v204 offset:47616
	ds_read_b64_tr_b16 v[152:153], v204 offset:47680
	ds_read_b64_tr_b16 v[150:151], v204 offset:43072
	ds_read_b64_tr_b16 v[170:171], v204 offset:52224
	ds_read_b64_tr_b16 v[172:173], v204 offset:56832
	ds_read_b64_tr_b16 v[156:157], v204 offset:56896
	ds_read_b64_tr_b16 v[154:155], v204 offset:52288
	ds_read_b64_tr_b16 v[174:175], v204 offset:61440
	ds_read_b64_tr_b16 v[176:177], v205 offset:32256
	ds_read_b64_tr_b16 v[160:161], v205 offset:32320
	ds_read_b64_tr_b16 v[158:159], v204 offset:61504
	v_max_f32_e32 v0, v99, v99
	v_max_f32_e32 v236, v98, v98
	v_max_f32_e32 v0, v236, v0
	v_max_f32_e32 v236, v83, v83
	v_max_f32_e32 v237, v82, v82
	v_max_f32_e32 v236, v237, v236
	v_max3_f32 v0, v0, v100, v101
	v_max3_f32 v236, v236, v84, v85
	v_max3_f32 v0, v0, v102, v103
	v_max3_f32 v236, v236, v86, v87
	v_max3_f32 v0, v0, v104, v105
	v_max3_f32 v236, v236, v88, v89
	v_max3_f32 v0, v0, v106, v107
	v_max3_f32 v236, v236, v90, v91
	v_max3_f32 v0, v0, v108, v109
	v_max3_f32 v236, v236, v92, v93
	v_max3_f32 v0, v0, v110, v111
	v_max3_f32 v236, v236, v94, v95
	v_max3_f32 v0, v0, v112, v113
	v_max3_f32 v236, v236, v96, v97
	v_fma_f32 v0, v0, s44, 0
	v_fma_f32 v236, v236, s44, 0
	v_max_f32_e32 v0, v0, v236
	v_mov_b32_e32 v209, v0
	v_mov_b32_e32 v236, v0
	s_nop 1
	v_permlane32_swap_b32_e32 v209, v236
	s_nop 1
	v_max_f32_e32 v0, v209, v236
	s_waitcnt lgkmcnt(14)
	v_cmp_gt_f32_e32 vcc, v0, v208
	s_cbranch_vccz .LBB0_252
	v_max_f32_e32 v0, v0, v0
	v_max_f32_e32 v209, v208, v208
	v_max_f32_e32 v209, v209, v0
	v_sub_f32_e32 v0, v208, v209
	v_exp_f32_e32 v0, v0
	v_mov_b32_e32 v208, v209
	v_pk_mul_f32 v[64:65], v[64:65], v[0:1] op_sel_hi:[1,0]
	v_pk_mul_f32 v[62:63], v[62:63], v[0:1] op_sel_hi:[1,0]
	v_pk_mul_f32 v[60:61], v[60:61], v[0:1] op_sel_hi:[1,0]
	v_pk_mul_f32 v[58:59], v[58:59], v[0:1] op_sel_hi:[1,0]
	v_pk_mul_f32 v[56:57], v[56:57], v[0:1] op_sel_hi:[1,0]
	v_pk_mul_f32 v[54:55], v[54:55], v[0:1] op_sel_hi:[1,0]
	v_pk_mul_f32 v[52:53], v[52:53], v[0:1] op_sel_hi:[1,0]
	v_pk_mul_f32 v[50:51], v[50:51], v[0:1] op_sel_hi:[1,0]
	v_pk_mul_f32 v[48:49], v[48:49], v[0:1] op_sel_hi:[1,0]
	v_pk_mul_f32 v[46:47], v[46:47], v[0:1] op_sel_hi:[1,0]
	v_pk_mul_f32 v[44:45], v[44:45], v[0:1] op_sel_hi:[1,0]
	v_pk_mul_f32 v[42:43], v[42:43], v[0:1] op_sel_hi:[1,0]
	v_pk_mul_f32 v[40:41], v[40:41], v[0:1] op_sel_hi:[1,0]
	v_pk_mul_f32 v[38:39], v[38:39], v[0:1] op_sel_hi:[1,0]
	v_pk_mul_f32 v[36:37], v[36:37], v[0:1] op_sel_hi:[1,0]
	v_pk_mul_f32 v[34:35], v[34:35], v[0:1] op_sel_hi:[1,0]
	v_pk_mul_f32 v[32:33], v[32:33], v[0:1] op_sel_hi:[1,0]
	v_pk_mul_f32 v[30:31], v[30:31], v[0:1] op_sel_hi:[1,0]
	v_pk_mul_f32 v[28:29], v[28:29], v[0:1] op_sel_hi:[1,0]
	v_pk_mul_f32 v[26:27], v[26:27], v[0:1] op_sel_hi:[1,0]
	v_pk_mul_f32 v[24:25], v[24:25], v[0:1] op_sel_hi:[1,0]
	v_pk_mul_f32 v[22:23], v[22:23], v[0:1] op_sel_hi:[1,0]
	v_pk_mul_f32 v[20:21], v[20:21], v[0:1] op_sel_hi:[1,0]
	v_pk_mul_f32 v[18:19], v[18:19], v[0:1] op_sel_hi:[1,0]
	v_pk_mul_f32 v[16:17], v[16:17], v[0:1] op_sel_hi:[1,0]
	v_pk_mul_f32 v[14:15], v[14:15], v[0:1] op_sel_hi:[1,0]
	v_pk_mul_f32 v[12:13], v[12:13], v[0:1] op_sel_hi:[1,0]
	v_pk_mul_f32 v[10:11], v[10:11], v[0:1] op_sel_hi:[1,0]
	v_pk_mul_f32 v[8:9], v[8:9], v[0:1] op_sel_hi:[1,0]
	v_pk_mul_f32 v[6:7], v[6:7], v[0:1] op_sel_hi:[1,0]
	v_pk_mul_f32 v[4:5], v[4:5], v[0:1] op_sel_hi:[1,0]
	v_pk_mul_f32 v[2:3], v[2:3], v[0:1] op_sel_hi:[1,0]
	v_mul_f32_e32 v203, v203, v0
	s_branch .LBB0_252
